# band attention far tiles: constant bias read issued ahead of the QK MFMAs (no LDS round trip on the serial chain), pk_adds ordered by MFMA result age with hipcc's 12 wait states kept
# speedup vs baseline: 1.0112x; 1.0112x over previous
.LBB0_454:
	s_cmp_le_i32 s23, s62
	s_cselect_b64 s[60:61], -1, 0
	s_cmp_ge_i32 s23, s63
	s_cselect_b64 s[66:67], -1, 0
	s_and_b64 s[60:61], s[60:61], s[66:67]
	s_andn2_b64 vcc, exec, s[60:61]
	s_cbranch_vccnz .LBB0_462
	ds_read_b32 v220, v3 offset:22528
	ds_read_b128 v[4:7], v165
	ds_read_b128 v[8:11], v165 offset:32
	ds_read_b128 v[12:15], v165 offset:4608
	ds_read_b128 v[130:133], v165 offset:64
	ds_read_b128 v[134:137], v165 offset:4640
	ds_read_b128 v[138:141], v165 offset:4672
	s_waitcnt lgkmcnt(5)
	v_mfma_f32_32x32x16_bf16 v[50:65], v[4:7], v[82:85], 0
	ds_read_b128 v[4:7], v165 offset:96
	ds_read_b128 v[142:145], v165 offset:4704
	s_waitcnt lgkmcnt(5)
	v_mfma_f32_32x32x16_bf16 v[66:81], v[12:15], v[82:85], 0
	v_mfma_f32_32x32x16_bf16 v[50:65], v[8:11], v[86:89], v[50:65]
	s_waitcnt lgkmcnt(3)
	v_mfma_f32_32x32x16_bf16 v[66:81], v[134:137], v[86:89], v[66:81]
	v_mfma_f32_32x32x16_bf16 v[50:65], v[130:133], v[90:93], v[50:65]
	s_waitcnt lgkmcnt(2)
	v_mfma_f32_32x32x16_bf16 v[66:81], v[138:141], v[90:93], v[66:81]
	s_waitcnt lgkmcnt(1)
	v_mfma_f32_32x32x16_bf16 v[50:65], v[4:7], v[94:97], v[50:65]
	s_waitcnt lgkmcnt(0)
	v_mfma_f32_32x32x16_bf16 v[66:81], v[142:145], v[94:97], v[66:81]
	s_cmp_lt_i32 s64, 3
	s_mov_b64 s[60:61], -1
	s_cbranch_scc0 .LBB0_457
	v_lshlrev_b32_e32 v186, 2, v119
	s_cmp_lt_i32 s64, 2
	s_cbranch_scc0 .Lbg_clamp
	ds_read_b32 v4, v186 offset:21504
	ds_read_b32 v5, v186 offset:21500
	ds_read_b32 v6, v186 offset:21496
	ds_read_b32 v7, v186 offset:21492
	ds_read_b32 v8, v186 offset:21488
	ds_read_b32 v9, v186 offset:21484
	ds_read_b32 v10, v186 offset:21480
	ds_read_b32 v11, v186 offset:21476
	ds_read_b32 v12, v186 offset:21440
	ds_read_b32 v13, v186 offset:21436
	ds_read_b32 v14, v186 offset:21432
	ds_read_b32 v15, v186 offset:21428
	ds_read_b32 v130, v186 offset:21424
	ds_read_b32 v131, v186 offset:21420
	ds_read_b32 v16, v186 offset:21416
	ds_read_b32 v17, v186 offset:21412
	ds_read_b32 v136, v186 offset:21376
	ds_read_b32 v137, v186 offset:21372
	ds_read_b32 v132, v186 offset:21368
	ds_read_b32 v133, v186 offset:21364
	ds_read_b32 v174, v186 offset:21360
	ds_read_b32 v175, v186 offset:21356
	ds_read_b32 v176, v186 offset:21352
	ds_read_b32 v177, v186 offset:21348
	ds_read_b32 v178, v186 offset:21312
	ds_read_b32 v179, v186 offset:21308
	ds_read_b32 v180, v186 offset:21304
	ds_read_b32 v181, v186 offset:21300
	ds_read_b32 v182, v186 offset:21296
	ds_read_b32 v183, v186 offset:21292
	ds_read_b32 v184, v186 offset:21288
	ds_read_b32 v185, v186 offset:21284
	s_branch .Lbg_tail

.LBB0_457:
	s_andn2_b64 vcc, exec, s[60:61]
	s_cbranch_vccnz .LBB0_459
	s_nop 6
	v_pk_add_f32 v[16:17], v[64:65], v[220:221] op_sel_hi:[1,0]
	v_pk_add_f32 v[130:131], v[62:63], v[220:221] op_sel_hi:[1,0]
	v_pk_add_f32 v[134:135], v[60:61], v[220:221] op_sel_hi:[1,0]
	v_pk_add_f32 v[138:139], v[58:59], v[220:221] op_sel_hi:[1,0]
	v_pk_add_f32 v[140:141], v[56:57], v[220:221] op_sel_hi:[1,0]
	v_pk_add_f32 v[142:143], v[54:55], v[220:221] op_sel_hi:[1,0]
	v_pk_add_f32 v[144:145], v[52:53], v[220:221] op_sel_hi:[1,0]
	v_pk_add_f32 v[146:147], v[50:51], v[220:221] op_sel_hi:[1,0]
	v_pk_add_f32 v[4:5], v[80:81], v[220:221] op_sel_hi:[1,0]
	v_pk_add_f32 v[6:7], v[78:79], v[220:221] op_sel_hi:[1,0]
	v_pk_add_f32 v[8:9], v[76:77], v[220:221] op_sel_hi:[1,0]
	v_pk_add_f32 v[10:11], v[74:75], v[220:221] op_sel_hi:[1,0]
	v_pk_add_f32 v[12:13], v[72:73], v[220:221] op_sel_hi:[1,0]
	v_pk_add_f32 v[14:15], v[70:71], v[220:221] op_sel_hi:[1,0]
	v_pk_add_f32 v[132:133], v[68:69], v[220:221] op_sel_hi:[1,0]
	v_pk_add_f32 v[136:137], v[66:67], v[220:221] op_sel_hi:[1,0]
